# v31 plus: the XCD's last arriver leaves the barrier without waiting for the completion of its two fire-and-forget generation adds
# baseline (speedup 1.0000x reference)
; __device__ __forceinline__ unsigned xb_ld(unsigned* p)              { return __hip_atomic_load(p, __ATOMIC_RELAXED, __HIP_MEMORY_SCOPE_AGENT); }
; __device__ __forceinline__ unsigned xb_add(unsigned* p, unsigned v) { return __hip_atomic_fetch_add(p, v, __ATOMIC_RELAXED, __HIP_MEMORY_SCOPE_AGENT); }
; #define XB_SPIN(cond, bar) do { unsigned _sp = 0; while (cond) { __builtin_amdgcn_s_sleep(1); \
;     if ((++_sp & 255u) == 0u) { if (xb_ld(&(bar)[XB_TMO])) break; if (_sp > XB_SPIN_CAP) { atomicAdd(&(bar)[XB_TMO], 1u); break; } } } } while (0)
; __device__ __forceinline__ void xcd_barrier(const XcdBarrier& b) {
;     ...
;             const unsigned og = xb_add(&bar[XB_TOP], 1u);
;             const unsigned tg = og / nx;
;             if (og + 1u == (tg + 1u) * nx) xb_add(&bar[XB_TOPGEN], 1u);
;             else XB_SPIN(xb_ld(&bar[XB_TOPGEN]) == tg, bar);
;             __builtin_amdgcn_fence(__ATOMIC_ACQUIRE, "agent");
;             xb_add(&bar[XB_XGEN(b.x)], 1u);
;             asm volatile("s_waitcnt vmcnt(0)" ::: "memory");
.LBB0_148:
	s_or_b64 exec, exec, s[12:13]
	s_mov_b64 s[12:13], exec
	v_mbcnt_lo_u32_b32 v0, s12, 0
	v_mbcnt_hi_u32_b32 v0, s13, v0
	v_cmp_eq_u32_e32 vcc, 0, v0
	s_and_saveexec_b64 s[14:15], vcc
	s_cbranch_execz .LBB0_150
	s_bcnt1_i32_b64 s12, s[12:13]
	v_mov_b32_e32 v0, 0x2000
	v_mov_b32_e32 v1, s12
	global_atomic_add v0, v1, s[10:11] offset:1024
.LBB0_150:
	s_or_b64 exec, exec, s[14:15]
.LBB0_151:
	s_or_b64 exec, exec, s[8:9]

; __device__ __forceinline__ unsigned xb_add(unsigned* p, unsigned v) { return __hip_atomic_fetch_add(p, v, __ATOMIC_RELAXED, __HIP_MEMORY_SCOPE_AGENT); }
; __device__ __forceinline__ void xcd_barrier(const XcdBarrier& b) {
;     ...
;             __builtin_amdgcn_fence(__ATOMIC_ACQUIRE, "agent");
;             xb_add(&bar[XB_XGEN(b.x)], 1u);
;             asm volatile("s_waitcnt vmcnt(0)" ::: "memory");
.LBB0_359:
	s_or_b64 exec, exec, s[10:11]
	s_mov_b64 s[10:11], exec
	v_mbcnt_lo_u32_b32 v0, s10, 0
	v_mbcnt_hi_u32_b32 v0, s11, v0
	v_cmp_eq_u32_e32 vcc, 0, v0
	s_and_saveexec_b64 s[12:13], vcc
	s_cbranch_execz .LBB0_361
	s_bcnt1_i32_b64 s10, s[10:11]
	v_mov_b32_e32 v0, 0x2000
	v_mov_b32_e32 v1, s10
	global_atomic_add v0, v1, s[8:9] offset:1024
.LBB0_361:
	s_or_b64 exec, exec, s[12:13]
.LBB0_362:
	s_or_b64 exec, exec, s[6:7]

; __device__ __forceinline__ unsigned xb_add(unsigned* p, unsigned v) { return __hip_atomic_fetch_add(p, v, __ATOMIC_RELAXED, __HIP_MEMORY_SCOPE_AGENT); }
; __device__ __forceinline__ void xcd_barrier(const XcdBarrier& b) {
;     ...
;             __builtin_amdgcn_fence(__ATOMIC_ACQUIRE, "agent");
;             xb_add(&bar[XB_XGEN(b.x)], 1u);
;             asm volatile("s_waitcnt vmcnt(0)" ::: "memory");
.LBB0_450:
	s_or_b64 exec, exec, s[22:23]
	s_mov_b64 s[22:23], exec
	v_mbcnt_lo_u32_b32 v0, s22, 0
	v_mbcnt_hi_u32_b32 v0, s23, v0
	v_cmp_eq_u32_e32 vcc, 0, v0
	s_and_saveexec_b64 s[28:29], vcc
	s_cbranch_execz .LBB0_452
	s_bcnt1_i32_b64 s11, s[22:23]
	v_readlane_b32 s12, v247, 11
	v_mov_b32_e32 v0, s11
	v_readlane_b32 s13, v247, 12
	s_nop 4
	global_atomic_add v173, v0, s[12:13]
.LBB0_452:
	s_or_b64 exec, exec, s[28:29]
.LBB0_453:
	s_or_b64 exec, exec, s[2:3]

; __device__ __forceinline__ unsigned xb_add(unsigned* p, unsigned v) { return __hip_atomic_fetch_add(p, v, __ATOMIC_RELAXED, __HIP_MEMORY_SCOPE_AGENT); }
; __device__ __forceinline__ void xcd_barrier(const XcdBarrier& b) {
;     ...
;             xb_add(&bar[XB_XGEN(b.x)], 1u);
;             asm volatile("s_waitcnt vmcnt(0)" ::: "memory");
.LBB0_639:
	s_or_b64 exec, exec, s[28:29]
.LBB0_640:
	s_or_b64 exec, exec, s[2:3]

; __device__ __forceinline__ unsigned xb_add(unsigned* p, unsigned v) { return __hip_atomic_fetch_add(p, v, __ATOMIC_RELAXED, __HIP_MEMORY_SCOPE_AGENT); }
; __device__ __forceinline__ void xcd_barrier(const XcdBarrier& b) {
;     ...
;             xb_add(&bar[XB_XGEN(b.x)], 1u);
;             asm volatile("s_waitcnt vmcnt(0)" ::: "memory");
.LBB0_729:
	s_or_b64 exec, exec, s[28:29]
.LBB0_730:
	s_or_b64 exec, exec, s[2:3]

; __device__ __forceinline__ unsigned xb_add(unsigned* p, unsigned v) { return __hip_atomic_fetch_add(p, v, __ATOMIC_RELAXED, __HIP_MEMORY_SCOPE_AGENT); }
; __device__ __forceinline__ void xcd_barrier(const XcdBarrier& b) {
;     ...
;             xb_add(&bar[XB_XGEN(b.x)], 1u);
;             asm volatile("s_waitcnt vmcnt(0)" ::: "memory");
.LBB0_1104:
	s_or_b64 exec, exec, s[28:29]
.LBB0_1105:
	s_or_b64 exec, exec, s[2:3]

; __device__ __forceinline__ unsigned xb_add(unsigned* p, unsigned v) { return __hip_atomic_fetch_add(p, v, __ATOMIC_RELAXED, __HIP_MEMORY_SCOPE_AGENT); }
; __device__ __forceinline__ void xcd_barrier(const XcdBarrier& b) {
;     ...
;             xb_add(&bar[XB_XGEN(b.x)], 1u);
;             asm volatile("s_waitcnt vmcnt(0)" ::: "memory");
.LBB0_1169:
	s_or_b64 exec, exec, s[28:29]
.LBB0_1170:
	s_or_b64 exec, exec, s[2:3]

; __device__ __forceinline__ unsigned xb_add(unsigned* p, unsigned v) { return __hip_atomic_fetch_add(p, v, __ATOMIC_RELAXED, __HIP_MEMORY_SCOPE_AGENT); }
; __device__ __forceinline__ void xcd_barrier(const XcdBarrier& b) {
;     ...
;             xb_add(&bar[XB_XGEN(b.x)], 1u);
;             asm volatile("s_waitcnt vmcnt(0)" ::: "memory");
.LBB0_1243:
	s_or_b64 exec, exec, s[28:29]
.LBB0_1244:
	s_or_b64 exec, exec, s[2:3]

; __device__ __forceinline__ unsigned xb_add(unsigned* p, unsigned v) { return __hip_atomic_fetch_add(p, v, __ATOMIC_RELAXED, __HIP_MEMORY_SCOPE_AGENT); }
; __device__ __forceinline__ void xcd_barrier(const XcdBarrier& b) {
;     ...
;             __builtin_amdgcn_fence(__ATOMIC_ACQUIRE, "agent");
;             xb_add(&bar[XB_XGEN(b.x)], 1u);
;             asm volatile("s_waitcnt vmcnt(0)" ::: "memory");
.LBB0_1420:
	s_or_b64 exec, exec, s[22:23]
	s_mov_b64 s[22:23], exec
	v_mbcnt_lo_u32_b32 v0, s22, 0
	v_mbcnt_hi_u32_b32 v0, s23, v0
	v_cmp_eq_u32_e32 vcc, 0, v0
	s_and_saveexec_b64 s[28:29], vcc
	s_cbranch_execz .LBB0_1422
	s_bcnt1_i32_b64 s6, s[22:23]
	v_readlane_b32 s16, v247, 11
	v_mov_b32_e32 v0, s6
	v_readlane_b32 s17, v247, 12
	s_nop 4
	global_atomic_add v173, v0, s[16:17]
.LBB0_1422:
	s_or_b64 exec, exec, s[28:29]
.LBB0_1423:
	s_or_b64 exec, exec, s[26:27]

; __device__ __forceinline__ unsigned xb_add(unsigned* p, unsigned v) { return __hip_atomic_fetch_add(p, v, __ATOMIC_RELAXED, __HIP_MEMORY_SCOPE_AGENT); }
; __device__ __forceinline__ void xcd_barrier(const XcdBarrier& b) {
;     ...
;             xb_add(&bar[XB_XGEN(b.x)], 1u);
;             asm volatile("s_waitcnt vmcnt(0)" ::: "memory");
.LBB0_1574:
	s_or_b64 exec, exec, s[28:29]
.LBB0_1575:
	s_or_b64 exec, exec, s[26:27]

; __device__ __forceinline__ unsigned xb_add(unsigned* p, unsigned v) { return __hip_atomic_fetch_add(p, v, __ATOMIC_RELAXED, __HIP_MEMORY_SCOPE_AGENT); }
; __device__ __forceinline__ void xcd_barrier(const XcdBarrier& b) {
;     ...
;             xb_add(&bar[XB_XGEN(b.x)], 1u);
;             asm volatile("s_waitcnt vmcnt(0)" ::: "memory");
.LBB0_1684:
	s_or_b64 exec, exec, s[28:29]
.LBB0_1685:
	s_or_b64 exec, exec, s[26:27]

; __device__ __forceinline__ unsigned xb_add(unsigned* p, unsigned v) { return __hip_atomic_fetch_add(p, v, __ATOMIC_RELAXED, __HIP_MEMORY_SCOPE_AGENT); }
; __device__ __forceinline__ void xcd_barrier(const XcdBarrier& b) {
;     ...
;             xb_add(&bar[XB_XGEN(b.x)], 1u);
;             asm volatile("s_waitcnt vmcnt(0)" ::: "memory");
.LBB0_1805:
	s_or_b64 exec, exec, s[28:29]
.LBB0_1806:
	s_or_b64 exec, exec, s[2:3]

; __device__ __forceinline__ unsigned xb_add(unsigned* p, unsigned v) { return __hip_atomic_fetch_add(p, v, __ATOMIC_RELAXED, __HIP_MEMORY_SCOPE_AGENT); }
; __device__ __forceinline__ void xcd_barrier(const XcdBarrier& b) {
;     ...
;             xb_add(&bar[XB_XGEN(b.x)], 1u);
;             asm volatile("s_waitcnt vmcnt(0)" ::: "memory");
.LBB0_1868:
	s_or_b64 exec, exec, s[28:29]
.LBB0_1869:
	s_or_b64 exec, exec, s[2:3]

; __device__ __forceinline__ unsigned xb_add(unsigned* p, unsigned v) { return __hip_atomic_fetch_add(p, v, __ATOMIC_RELAXED, __HIP_MEMORY_SCOPE_AGENT); }
; __device__ __forceinline__ void xcd_barrier(const XcdBarrier& b) {
;     ...
;             xb_add(&bar[XB_XGEN(b.x)], 1u);
;             asm volatile("s_waitcnt vmcnt(0)" ::: "memory");
.LBB0_2020:
	s_or_b64 exec, exec, s[28:29]
.LBB0_2021:
	s_or_b64 exec, exec, s[2:3]

; __device__ __forceinline__ unsigned xb_add(unsigned* p, unsigned v) { return __hip_atomic_fetch_add(p, v, __ATOMIC_RELAXED, __HIP_MEMORY_SCOPE_AGENT); }
; __device__ __forceinline__ void xcd_barrier(const XcdBarrier& b) {
;     ...
;             __builtin_amdgcn_fence(__ATOMIC_ACQUIRE, "agent");
;             xb_add(&bar[XB_XGEN(b.x)], 1u);
;             asm volatile("s_waitcnt vmcnt(0)" ::: "memory");
.LBB0_2193:
	s_or_b64 exec, exec, s[22:23]
	s_mov_b64 s[22:23], exec
	v_mbcnt_lo_u32_b32 v0, s22, 0
	v_mbcnt_hi_u32_b32 v0, s23, v0
	v_cmp_eq_u32_e32 vcc, 0, v0
	s_and_saveexec_b64 s[26:27], vcc
	s_cbranch_execz .LBB0_2195
	s_bcnt1_i32_b64 s6, s[22:23]
	v_readlane_b32 s14, v247, 11
	v_mov_b32_e32 v0, s6
	v_readlane_b32 s15, v247, 12
	s_nop 4
	global_atomic_add v173, v0, s[14:15]
.LBB0_2195:
	s_or_b64 exec, exec, s[26:27]
.LBB0_2196:
	s_or_b64 exec, exec, s[2:3]

; __device__ __forceinline__ unsigned xb_add(unsigned* p, unsigned v) { return __hip_atomic_fetch_add(p, v, __ATOMIC_RELAXED, __HIP_MEMORY_SCOPE_AGENT); }
; __device__ __forceinline__ void xcd_barrier(const XcdBarrier& b) {
;     ...
;             __builtin_amdgcn_fence(__ATOMIC_ACQUIRE, "agent");
;             xb_add(&bar[XB_XGEN(b.x)], 1u);
;             asm volatile("s_waitcnt vmcnt(0)" ::: "memory");
.LBB0_2289:
	s_or_b64 exec, exec, s[22:23]
	s_mov_b64 s[22:23], exec
	v_mbcnt_lo_u32_b32 v0, s22, 0
	v_mbcnt_hi_u32_b32 v0, s23, v0
	v_cmp_eq_u32_e32 vcc, 0, v0
	s_and_saveexec_b64 s[36:37], vcc
	s_cbranch_execz .LBB0_2291
	s_bcnt1_i32_b64 s11, s[22:23]
	v_readlane_b32 s14, v247, 11
	v_mov_b32_e32 v0, s11
	v_readlane_b32 s15, v247, 12
	s_nop 4
	global_atomic_add v173, v0, s[14:15]
.LBB0_2291:
	s_or_b64 exec, exec, s[36:37]
.LBB0_2292:
	s_or_b64 exec, exec, s[2:3]
	s_mov_b32 s14, 0x87000

; __device__ __forceinline__ unsigned xb_add(unsigned* p, unsigned v) { return __hip_atomic_fetch_add(p, v, __ATOMIC_RELAXED, __HIP_MEMORY_SCOPE_AGENT); }
; __device__ __forceinline__ void xcd_barrier(const XcdBarrier& b) {
;     ...
;             __builtin_amdgcn_fence(__ATOMIC_ACQUIRE, "agent");
;             xb_add(&bar[XB_XGEN(b.x)], 1u);
;             asm volatile("s_waitcnt vmcnt(0)" ::: "memory");
.LBB0_2581:
	s_or_b64 exec, exec, s[22:23]
	s_mov_b64 s[22:23], exec
	v_mbcnt_lo_u32_b32 v0, s22, 0
	v_mbcnt_hi_u32_b32 v0, s23, v0
	v_cmp_eq_u32_e32 vcc, 0, v0
	s_and_saveexec_b64 s[30:31], vcc
	s_cbranch_execnz .LBB0_2582
	s_getpc_b64 s[98:99]

; __device__ __forceinline__ unsigned xb_add(unsigned* p, unsigned v) { return __hip_atomic_fetch_add(p, v, __ATOMIC_RELAXED, __HIP_MEMORY_SCOPE_AGENT); }
; __device__ __forceinline__ void xcd_barrier(const XcdBarrier& b) {
;     ...
;             __builtin_amdgcn_fence(__ATOMIC_ACQUIRE, "agent");
;             xb_add(&bar[XB_XGEN(b.x)], 1u);
;             asm volatile("s_waitcnt vmcnt(0)" ::: "memory");
.LBB0_2649:
	s_or_b64 exec, exec, s[2:3]
	s_mov_b64 s[2:3], exec
	v_mbcnt_lo_u32_b32 v0, s2, 0
	v_mbcnt_hi_u32_b32 v0, s3, v0
	v_cmp_eq_u32_e32 vcc, 0, v0
	s_and_saveexec_b64 s[4:5], vcc
	s_cbranch_execz .LBB0_2651
	s_bcnt1_i32_b64 s2, s[2:3]
	v_mov_b32_e32 v1, s2
	v_readlane_b32 s2, v247, 11
	v_mov_b32_e32 v0, 0
	v_readlane_b32 s3, v247, 12
	s_nop 4
	global_atomic_add v0, v1, s[2:3]
.LBB0_2651:
	s_or_b64 exec, exec, s[4:5]
.LBB0_2652:
	s_or_b64 exec, exec, s[0:1]
